# out-proj epilogue: second-half residual loads hoisted above first-half stores; cooperative grid.sync replaced by one-way flag publication
# speedup vs baseline: 1.0206x; 1.0056x over previous
.LBB0_12:
	s_cmp_lg_u32 s96, 0
	s_cbranch_scc1 .Lgs_skip
	s_waitcnt vmcnt(0)
	s_barrier
	v_cmp_eq_u32_e32 vcc, 0, v2
	s_and_saveexec_b64 s[2:3], vcc
	s_cbranch_execz .Lgs_pub_done
	buffer_wbl2 sc1
	s_waitcnt vmcnt(0)
	v_mov_b32_e32 v0, 0
	v_mov_b32_e32 v4, 0x5a17c0de
	v_mov_b32_e32 v5, 0x7e11f1a9
	global_store_dwordx2 v0, v[4:5], s[18:19] offset:2048 sc1
	s_waitcnt vmcnt(0)

.Lgs_skip:
	s_add_u32 s0, s18, 0x4000
	s_addc_u32 s1, s19, 0
	v_writelane_b32 v243, s0, 4
	s_nop 0
	v_writelane_b32 v243, s1, 5
	s_getreg_b32 s0, hwreg(HW_REG_XCC_ID, 0, 4)
	s_and_b32 s41, s0, 15
	s_lshr_b32 s97, s14, 6
	v_readlane_b32 s12, v243, 2
	v_readlane_b32 s13, v243, 3
	s_mov_b32 s0, s97
	v_mbcnt_lo_u32_b32 v9, -1, 0
	v_mbcnt_hi_u32_b32 v9, -1, v9
	s_mov_b32 s42, s96
	v_lshl_or_b32 v48, s0, 6, v9
	v_readlane_b32 s0, v243, 0
	v_ashrrev_i32_e32 v49, 6, v48
	s_lshl_b32 s33, s42, 3
	v_and_b32_e32 v8, 63, v9
	v_readlane_b32 s1, v243, 1
	s_mov_b32 s43, s0
	v_add_u32_e32 v10, s33, v49
	s_movk_i32 s2, 0x7d0
	s_load_dwordx2 s[0:1], s[12:13], 0xa8
	s_lshl_b32 s14, s43, 3
	v_cmp_gt_i32_e32 vcc, s2, v10
	v_lshlrev_b32_e32 v12, 4, v8
	s_waitcnt lgkmcnt(0)
	s_and_saveexec_b64 s[16:17], vcc
	v_writelane_b32 v243, s96, 6
	s_cbranch_execz .LBB0_67
	s_load_dwordx4 s[4:7], s[12:13], 0x78
	s_load_dwordx4 s[8:11], s[12:13], 0x38
	s_add_u32 s2, s0, 0x100000
	v_and_b32_e32 v3, 7, v9
	s_addc_u32 s3, s1, 0
	v_lshlrev_b32_e32 v14, 5, v3
	v_mov_b32_e32 v15, 0
	v_lshlrev_b32_e32 v0, 2, v9
	s_waitcnt lgkmcnt(0)
	s_cmp_lg_u64 s[4:5], 0
	v_lshl_add_u64 v[16:17], s[4:5], 0, v[14:15]
	s_mov_b64 s[4:5], 0x1000
	v_and_b32_e32 v0, 0x7c, v0
	v_mov_b32_e32 v1, v15
	v_lshl_add_u64 v[18:19], v[16:17], 0, s[4:5]
	v_lshl_add_u64 v[20:21], s[6:7], 0, v[0:1]
	s_mov_b64 s[4:5], 0x200000
	v_lshl_add_u64 v[22:23], v[20:21], 0, s[4:5]
	s_load_dwordx2 s[4:5], s[12:13], 0x98
	s_load_dwordx8 s[44:51], s[12:13], 0x18
	s_cselect_b64 s[18:19], -1, 0
	s_add_u32 s20, s0, 0xd00000
	v_lshrrev_b32_e32 v11, 5, v8
	s_addc_u32 s21, s1, 0
	v_lshl_add_u32 v2, v49, 14, 0
	v_mul_u32_u24_e32 v4, 0x84, v11
	v_lshrrev_b32_e32 v51, 3, v8
	s_add_u32 s22, s0, 0xe00000
	v_add3_u32 v50, v2, v0, v4
	v_mul_u32_u24_e32 v4, 0x420, v3
	v_lshlrev_b32_e32 v5, 2, v51
	s_addc_u32 s23, s1, 0
	v_add3_u32 v52, v2, v4, v5
	s_waitcnt lgkmcnt(0)
	v_lshl_add_u64 v[26:27], s[4:5], 0, v[0:1]
	v_lshlrev_b32_e32 v2, 4, v3
	v_mov_b32_e32 v3, v15
	s_cmp_lg_u64 s[50:51], 0
	v_lshl_add_u64 v[32:33], s[10:11], 0, v[0:1]
	v_lshl_add_u64 v[36:37], s[8:9], 0, v[0:1]
	v_lshl_add_u64 v[40:41], s[46:47], 0, v[0:1]
	v_lshlrev_b32_e32 v0, 2, v49
	v_lshl_add_u64 v[4:5], s[0:1], 0, v[2:3]
	s_mov_b64 s[4:5], 0xf00000
	s_cselect_b64 s[24:25], -1, 0
	s_cmp_lg_u64 s[48:49], 0
	v_lshl_add_u32 v0, s42, 5, v0
	v_mov_b32_e32 v13, v15
	v_lshl_add_u64 v[28:29], v[4:5], 0, s[4:5]
	v_lshlrev_b32_e32 v4, 5, v8
	s_cselect_b64 s[10:11], -1, 0
	s_cmp_lg_u64 s[44:45], 0
	v_add_u32_e32 v58, 0xfffff8c0, v0
	v_mov_b32_e32 v0, 0xffffc000
	v_or_b32_e32 v53, 8, v51
	v_or_b32_e32 v54, 16, v51
	v_or_b32_e32 v55, 24, v51
	v_lshl_add_u64 v[24:25], s[2:3], 0, v[12:13]
	v_lshl_add_u64 v[30:31], s[50:51], 0, v[14:15]
	v_bfe_u32 v13, v9, 1, 2
	v_and_b32_e32 v56, 32, v4
	v_lshl_add_u64 v[34:35], s[48:49], 0, v[14:15]
	v_and_b32_e32 v57, 0xe0, v4
	s_cselect_b64 s[8:9], -1, 0
	v_lshl_add_u64 v[38:39], s[44:45], 0, v[14:15]
	v_lshl_add_u64 v[42:43], s[2:3], 0, v[2:3]
	s_lshl_b32 s15, s43, 5
	v_lshl_add_u32 v59, v10, 5, v0
	s_lshl_b32 s44, s43, 8
	s_movk_i32 s45, 0x2000
	s_movk_i32 s46, 0x4000
	s_movk_i32 s47, 0x6000
	s_mov_b32 s48, 0x8000
	s_mov_b32 s49, 0xa000
	s_mov_b32 s50, 0xc000
	s_mov_b32 s51, 0xe000
	s_mov_b32 s52, 0x10000
	s_mov_b32 s53, 0x12000
	s_mov_b32 s54, 0x14000
	s_mov_b32 s55, 0x16000
	s_mov_b32 s56, 0x18000
	s_mov_b32 s57, 0x19000
	s_mov_b32 s58, 0x1a000
	s_mov_b32 s59, 0x1b000
	s_mov_b32 s60, 0x1c000
	s_mov_b32 s61, 0x1e000
	s_mov_b32 s62, 0x1f000
	s_movk_i32 s63, 0x670
	s_movk_i32 s64, 0x4cf
	s_movk_i32 s65, 0x5cf
	s_movk_i32 s66, 0x62f
	s_movk_i32 s67, 0x66f
	s_mov_b32 s69, 0x20000
	s_mov_b32 s70, 0x22000
	s_mov_b32 s71, 0x24000
	s_mov_b32 s72, 0x26000
	s_mov_b32 s73, 0x28000
	s_mov_b32 s74, 0x2a000
	s_mov_b32 s75, 0x2c000
	s_mov_b32 s76, 0x2e000
	s_mov_b32 s77, 0x30000
	s_mov_b32 s78, 0x32000
	s_mov_b32 s79, 0x34000
	s_mov_b32 s80, 0x36000
	s_mov_b32 s81, 0x38000
	s_mov_b32 s82, 0x3a000
	s_mov_b32 s83, 0x3c000
	s_mov_b32 s84, 0x3e000
	s_movk_i32 s85, 0x3ff8
	s_movk_i32 s86, 0xab
	s_mov_b32 s87, 0x21000
	s_mov_b32 s88, 0x25000
	s_mov_b32 s89, 0x27000
	s_mov_b32 s90, 0x2b000
	s_mov_b32 s91, 0x2d000
	s_mov_b32 s92, 0x3531dec1
	s_movk_i32 s93, 0x4d
	v_mov_b32_e32 v60, 0xc0
	v_mov_b32_e32 v61, v10
	s_movk_i32 s94, 0x2680
	s_movk_i32 s95, 0x7cf
	s_mov_b64 s[26:27], 0
	s_mov_b32 s4, 0
	s_branch .LBB0_31

.LBB0_106:
	s_or_b64 exec, exec, s[6:7]
	v_mbcnt_lo_u32_b32 v0, -1, 0
	v_mbcnt_hi_u32_b32 v0, -1, v0
	v_lshl_or_b32 v0, s97, 6, v0
	v_cmp_eq_u32_e32 vcc, 0, v0
	s_and_saveexec_b64 s[6:7], vcc
	s_cbranch_execz .Lfw_done
	v_readlane_b32 s2, v243, 4
	v_readlane_b32 s3, v243, 5
	s_mov_b32 s8, 0
	v_mov_b32_e32 v1, 0
	v_mov_b32_e32 v4, 0x7e11f1a9
	s_sub_u32 s10, s2, 0x3800
	s_subb_u32 s11, s3, 0
	s_nop 4
.Lfw_poll:
	global_load_dwordx2 v[2:3], v1, s[10:11] sc1
	s_waitcnt vmcnt(0)
	v_cmp_eq_u32_e32 vcc, 0x5a17c0de, v2
	v_cmp_eq_u32_e64 s[4:5], v4, v3
	s_and_b64 vcc, vcc, s[4:5]
	s_cbranch_vccnz .Lfw_ok
	s_sleep 2
	s_add_u32 s8, s8, 1
	s_cmp_lt_u32 s8, 0x100000
	s_cbranch_scc1 .Lfw_poll
.Lfw_ok:
	s_lshl_b32 s4, s41, 8
	v_mov_b32_e32 v0, s4
	v_mov_b32_e32 v1, 1
	global_atomic_add v0, v1, s[2:3] offset:1024

.LBB0_658:
	s_lshl_b32 s1, s42, 8
	v_lshl_or_b32 v168, s0, 8, v180
	v_add_u32_e32 v170, s1, v178
	v_ashrrev_i32_e32 v169, 31, v168
	v_ashrrev_i32_e32 v171, 31, v170
	v_lshl_add_u64 v[166:167], v[168:169], 1, s[4:5]
	v_lshlrev_b64 v[128:129], 11, v[170:171]
	v_lshl_add_u64 v[128:129], v[166:167], 0, v[128:129]
	global_load_dwordx4 v[174:177], v[128:129], off nt
	global_load_dwordx4 v[152:155], v[128:129], off offset:256 nt
	v_or_b32_e32 v128, 16, v170
	v_ashrrev_i32_e32 v129, 31, v128
	v_lshlrev_b64 v[128:129], 11, v[128:129]
	v_lshl_add_u64 v[128:129], v[166:167], 0, v[128:129]
	global_load_dwordx4 v[148:151], v[128:129], off nt
	global_load_dwordx4 v[144:147], v[128:129], off offset:256 nt
	v_or_b32_e32 v128, 32, v170
	v_ashrrev_i32_e32 v129, 31, v128
	v_lshlrev_b64 v[128:129], 11, v[128:129]
	v_lshl_add_u64 v[128:129], v[166:167], 0, v[128:129]
	global_load_dwordx4 v[140:143], v[128:129], off nt
	global_load_dwordx4 v[136:139], v[128:129], off offset:256 nt
	v_or_b32_e32 v128, 48, v170
	v_ashrrev_i32_e32 v129, 31, v128
	v_lshlrev_b64 v[128:129], 11, v[128:129]
	v_lshl_add_u64 v[128:129], v[166:167], 0, v[128:129]
	global_load_dwordx4 v[132:135], v[128:129], off nt
	s_nop 0
	global_load_dwordx4 v[128:131], v[128:129], off offset:256 nt
	v_add_u32_e32 v162, 0x80, v170
	v_ashrrev_i32_e32 v163, 31, v162
	v_lshlrev_b64 v[160:161], 11, v[162:163]
	v_lshl_add_u64 v[160:161], v[166:167], 0, v[160:161]
	global_load_dwordx4 v[214:217], v[160:161], off nt
	global_load_dwordx4 v[218:221], v[160:161], off offset:256 nt
	v_add_u32_e32 v162, 0x90, v170
	v_ashrrev_i32_e32 v163, 31, v162
	v_lshlrev_b64 v[160:161], 11, v[162:163]
	v_lshl_add_u64 v[160:161], v[166:167], 0, v[160:161]
	global_load_dwordx4 v[222:225], v[160:161], off nt
	global_load_dwordx4 v[226:229], v[160:161], off offset:256 nt
	v_add_u32_e32 v162, 0xa0, v170
	v_ashrrev_i32_e32 v163, 31, v162
	v_lshlrev_b64 v[160:161], 11, v[162:163]
	v_lshl_add_u64 v[160:161], v[166:167], 0, v[160:161]
	global_load_dwordx4 v[230:233], v[160:161], off nt
	global_load_dwordx4 v[234:237], v[160:161], off offset:256 nt
	v_add_u32_e32 v162, 0xb0, v170
	v_ashrrev_i32_e32 v163, 31, v162
	v_lshlrev_b64 v[160:161], 11, v[162:163]
	v_lshl_add_u64 v[160:161], v[166:167], 0, v[160:161]
	global_load_dwordx4 v[238:241], v[160:161], off nt
	global_load_dwordx4 v[156:159], v[160:161], off offset:256 nt
	s_waitcnt vmcnt(8)
	v_lshlrev_b32_e32 v186, 16, v174
	v_and_b32_e32 v187, 0xffff0000, v174
	v_lshlrev_b32_e32 v188, 16, v175
	v_and_b32_e32 v189, 0xffff0000, v175
	v_lshlrev_b32_e32 v190, 16, v176
	v_and_b32_e32 v191, 0xffff0000, v176
	v_lshlrev_b32_e32 v176, 16, v177
	v_and_b32_e32 v177, 0xffff0000, v177
	v_lshlrev_b64 v[174:175], 10, v[170:171]
	v_lshl_add_u64 v[192:193], v[174:175], 0, v[168:169]
	v_pk_add_f32 v[122:123], v[122:123], v[176:177]
	v_cndmask_b32_e64 v176, 0, 1, s[18:19]
	v_pk_add_f32 v[126:127], v[126:127], v[188:189]
	v_pk_add_f32 v[124:125], v[124:125], v[186:187]
	v_pk_add_f32 v[120:121], v[120:121], v[190:191]
	v_cmp_ne_u32_e64 s[42:43], 1, v176
	s_andn2_b64 vcc, exec, s[18:19]
	v_lshl_add_u64 v[176:177], v[192:193], 2, s[10:11]
	s_cbranch_vccnz .LBB0_660
	global_store_dwordx4 v[176:177], v[124:127], off
	global_store_dwordx4 v[176:177], v[120:123], off offset:16

.LBB0_707:
	v_add_u32_e32 v98, 0x80, v170
	v_ashrrev_i32_e32 v99, 31, v98
	v_lshlrev_b64 v[64:65], 11, v[98:99]
	v_add_u32_e32 v96, 0x90, v170
	v_lshl_add_u64 v[64:65], v[166:167], 0, v[64:65]
	v_ashrrev_i32_e32 v97, 31, v96
	s_waitcnt vmcnt(8)
	v_mov_b64_e32 v[100:101], v[214:215]
	v_mov_b64_e32 v[102:103], v[216:217]
	v_mov_b64_e32 v[88:89], v[218:219]
	v_mov_b64_e32 v[90:91], v[220:221]
	v_lshlrev_b64 v[64:65], 11, v[96:97]
	v_add_u32_e32 v94, 0xa0, v170
	v_lshl_add_u64 v[64:65], v[166:167], 0, v[64:65]
	v_ashrrev_i32_e32 v95, 31, v94
	v_mov_b64_e32 v[84:85], v[222:223]
	v_mov_b64_e32 v[86:87], v[224:225]
	v_mov_b64_e32 v[80:81], v[226:227]
	v_mov_b64_e32 v[82:83], v[228:229]
	v_lshlrev_b64 v[64:65], 11, v[94:95]
	v_add_u32_e32 v92, 0xb0, v170
	v_lshl_add_u64 v[64:65], v[166:167], 0, v[64:65]
	v_ashrrev_i32_e32 v93, 31, v92
	v_mov_b64_e32 v[76:77], v[230:231]
	v_mov_b64_e32 v[78:79], v[232:233]
	v_mov_b64_e32 v[72:73], v[234:235]
	v_mov_b64_e32 v[74:75], v[236:237]
	v_lshlrev_b64 v[64:65], 11, v[92:93]
	v_lshl_add_u64 v[64:65], v[166:167], 0, v[64:65]
	v_mov_b64_e32 v[68:69], v[238:239]
	v_mov_b64_e32 v[70:71], v[240:241]
	v_mov_b64_e32 v[64:65], v[156:157]
	v_mov_b64_e32 v[66:67], v[158:159]
	s_nop 0
	v_lshlrev_b32_e32 v104, 16, v100
	v_and_b32_e32 v105, 0xffff0000, v100
	v_lshlrev_b32_e32 v106, 16, v101
	v_and_b32_e32 v107, 0xffff0000, v101
	v_lshlrev_b64 v[100:101], 10, v[98:99]
	v_lshlrev_b32_e32 v108, 16, v102
	v_and_b32_e32 v109, 0xffff0000, v102
	v_lshlrev_b32_e32 v102, 16, v103
	v_and_b32_e32 v103, 0xffff0000, v103
	v_lshl_add_u64 v[110:111], v[100:101], 0, v[168:169]
	v_pk_add_f32 v[62:63], v[62:63], v[106:107]
	v_pk_add_f32 v[60:61], v[60:61], v[104:105]
	v_pk_add_f32 v[58:59], v[58:59], v[102:103]
	v_pk_add_f32 v[56:57], v[56:57], v[108:109]
	s_and_b64 vcc, exec, s[42:43]
	v_lshl_add_u64 v[102:103], v[110:111], 2, s[10:11]
	s_cbranch_vccnz .LBB0_709
	global_store_dwordx4 v[102:103], v[60:63], off
	global_store_dwordx4 v[102:103], v[56:59], off offset:16

.LBB0_711:
	s_nop 0
	v_lshlrev_b32_e32 v56, 16, v88
	v_and_b32_e32 v57, 0xffff0000, v88
	v_lshlrev_b32_e32 v58, 16, v89
	v_and_b32_e32 v59, 0xffff0000, v89
	v_lshlrev_b32_e32 v60, 16, v90
	v_and_b32_e32 v61, 0xffff0000, v90
	v_lshlrev_b32_e32 v62, 16, v91
	v_and_b32_e32 v63, 0xffff0000, v91
	v_pk_add_f32 v[54:55], v[54:55], v[58:59]
	v_pk_add_f32 v[52:53], v[52:53], v[56:57]
	v_pk_add_f32 v[50:51], v[50:51], v[62:63]
	s_and_b64 vcc, exec, s[42:43]
	v_pk_add_f32 v[48:49], v[48:49], v[60:61]
	s_cbranch_vccnz .LBB0_713
	global_store_dwordx4 v[102:103], v[52:55], off offset:512
	global_store_dwordx4 v[102:103], v[48:51], off offset:528

.LBB0_719:
	v_lshlrev_b64 v[48:49], 10, v[96:97]
	s_nop 0
	v_lshlrev_b32_e32 v50, 16, v84
	v_and_b32_e32 v51, 0xffff0000, v84
	v_lshlrev_b32_e32 v54, 16, v85
	v_and_b32_e32 v55, 0xffff0000, v85
	v_lshlrev_b32_e32 v56, 16, v86
	v_and_b32_e32 v57, 0xffff0000, v86
	v_lshlrev_b32_e32 v58, 16, v87
	v_and_b32_e32 v59, 0xffff0000, v87
	v_lshl_add_u64 v[52:53], v[48:49], 0, v[168:169]
	v_pk_add_f32 v[46:47], v[46:47], v[54:55]
	v_pk_add_f32 v[44:45], v[44:45], v[50:51]
	v_pk_add_f32 v[42:43], v[42:43], v[58:59]
	v_pk_add_f32 v[40:41], v[40:41], v[56:57]
	s_and_b64 vcc, exec, s[42:43]
	v_lshl_add_u64 v[50:51], v[52:53], 2, s[10:11]
	s_cbranch_vccnz .LBB0_721
	s_mov_b64 s[44:45], s[6:7]
	global_store_dwordx4 v[50:51], v[44:47], off
	global_store_dwordx4 v[50:51], v[40:43], off offset:16

.LBB0_724:
	s_nop 0
	v_lshlrev_b32_e32 v40, 16, v80
	v_and_b32_e32 v41, 0xffff0000, v80
	v_lshlrev_b32_e32 v42, 16, v81
	v_and_b32_e32 v43, 0xffff0000, v81
	v_lshlrev_b32_e32 v44, 16, v82
	v_and_b32_e32 v45, 0xffff0000, v82
	v_lshlrev_b32_e32 v46, 16, v83
	v_and_b32_e32 v47, 0xffff0000, v83
	v_pk_add_f32 v[38:39], v[38:39], v[42:43]
	v_pk_add_f32 v[36:37], v[36:37], v[40:41]
	v_pk_add_f32 v[34:35], v[34:35], v[46:47]
	s_and_b64 vcc, exec, s[42:43]
	v_pk_add_f32 v[32:33], v[32:33], v[44:45]
	s_cbranch_vccnz .LBB0_726
	global_store_dwordx4 v[50:51], v[36:39], off offset:512
	global_store_dwordx4 v[50:51], v[32:35], off offset:528

.LBB0_732:
	v_lshlrev_b64 v[32:33], 10, v[94:95]
	s_nop 0
	v_lshlrev_b32_e32 v34, 16, v76
	v_and_b32_e32 v35, 0xffff0000, v76
	v_lshlrev_b32_e32 v38, 16, v77
	v_and_b32_e32 v39, 0xffff0000, v77
	v_lshlrev_b32_e32 v40, 16, v78
	v_and_b32_e32 v41, 0xffff0000, v78
	v_lshlrev_b32_e32 v42, 16, v79
	v_and_b32_e32 v43, 0xffff0000, v79
	v_lshl_add_u64 v[36:37], v[32:33], 0, v[168:169]
	v_pk_add_f32 v[30:31], v[30:31], v[38:39]
	v_pk_add_f32 v[28:29], v[28:29], v[34:35]
	v_pk_add_f32 v[26:27], v[26:27], v[42:43]
	v_pk_add_f32 v[24:25], v[24:25], v[40:41]
	s_and_b64 vcc, exec, s[42:43]
	v_lshl_add_u64 v[34:35], v[36:37], 2, s[10:11]
	s_cbranch_vccnz .LBB0_734
	s_mov_b64 s[44:45], s[6:7]
	global_store_dwordx4 v[34:35], v[28:31], off
	global_store_dwordx4 v[34:35], v[24:27], off offset:16

.LBB0_737:
	s_nop 0
	v_lshlrev_b32_e32 v24, 16, v72
	v_and_b32_e32 v25, 0xffff0000, v72
	v_lshlrev_b32_e32 v26, 16, v73
	v_and_b32_e32 v27, 0xffff0000, v73
	v_lshlrev_b32_e32 v28, 16, v74
	v_and_b32_e32 v29, 0xffff0000, v74
	v_lshlrev_b32_e32 v30, 16, v75
	v_and_b32_e32 v31, 0xffff0000, v75
	v_pk_add_f32 v[22:23], v[22:23], v[26:27]
	v_pk_add_f32 v[20:21], v[20:21], v[24:25]
	v_pk_add_f32 v[18:19], v[18:19], v[30:31]
	s_and_b64 vcc, exec, s[42:43]
	v_pk_add_f32 v[16:17], v[16:17], v[28:29]
	s_cbranch_vccnz .LBB0_739
	global_store_dwordx4 v[34:35], v[20:23], off offset:512
	global_store_dwordx4 v[34:35], v[16:19], off offset:528

.LBB0_745:
	v_lshlrev_b64 v[16:17], 10, v[92:93]
	s_nop 0
	v_lshlrev_b32_e32 v18, 16, v68
	v_and_b32_e32 v19, 0xffff0000, v68
	v_lshlrev_b32_e32 v22, 16, v69
	v_and_b32_e32 v23, 0xffff0000, v69
	v_lshlrev_b32_e32 v24, 16, v70
	v_and_b32_e32 v25, 0xffff0000, v70
	v_lshlrev_b32_e32 v26, 16, v71
	v_and_b32_e32 v27, 0xffff0000, v71
	v_lshl_add_u64 v[20:21], v[16:17], 0, v[168:169]
	v_pk_add_f32 v[14:15], v[14:15], v[22:23]
	v_pk_add_f32 v[12:13], v[12:13], v[18:19]
	v_pk_add_f32 v[10:11], v[10:11], v[26:27]
	v_pk_add_f32 v[8:9], v[8:9], v[24:25]
	s_and_b64 vcc, exec, s[42:43]
	v_lshl_add_u64 v[18:19], v[20:21], 2, s[10:11]
	s_cbranch_vccnz .LBB0_747
	s_mov_b64 s[44:45], s[6:7]
	global_store_dwordx4 v[18:19], v[12:15], off
	global_store_dwordx4 v[18:19], v[8:11], off offset:16

.LBB0_750:
	s_nop 0
	v_lshlrev_b32_e32 v8, 16, v64
	v_and_b32_e32 v9, 0xffff0000, v64
	v_lshlrev_b32_e32 v10, 16, v65
	v_and_b32_e32 v11, 0xffff0000, v65
	v_lshlrev_b32_e32 v12, 16, v66
	v_and_b32_e32 v13, 0xffff0000, v66
	v_lshlrev_b32_e32 v14, 16, v67
	v_and_b32_e32 v15, 0xffff0000, v67
	v_pk_add_f32 v[6:7], v[6:7], v[10:11]
	v_pk_add_f32 v[4:5], v[4:5], v[8:9]
	v_pk_add_f32 v[2:3], v[2:3], v[14:15]
	s_and_b64 vcc, exec, s[42:43]
	v_pk_add_f32 v[0:1], v[0:1], v[12:13]
	s_cbranch_vccnz .LBB0_752
	global_store_dwordx4 v[18:19], v[4:7], off offset:512
	global_store_dwordx4 v[18:19], v[0:3], off offset:528

.LBB0_803:
	v_readlane_b32 s2, v243, 6
	v_readlane_b32 s3, v243, 41
	s_mov_b64 exec, -1
	s_or_b32 s2, s2, s3
	s_cmp_lg_u32 s2, 0
	s_cbranch_scc1 .Lflag_clr_done
	v_mbcnt_lo_u32_b32 v0, -1, 0
	v_mbcnt_hi_u32_b32 v0, -1, v0
	v_cmp_eq_u32_e32 vcc, 0, v0
	s_and_saveexec_b64 s[6:7], vcc
	v_readlane_b32 s2, v243, 4
	v_readlane_b32 s3, v243, 5
	v_mov_b32_e32 v1, 0
	v_mov_b32_e32 v2, 0
	v_mov_b32_e32 v3, 0
	s_sub_u32 s10, s2, 0x3800
	s_subb_u32 s11, s3, 0
	s_nop 4
	global_store_dwordx2 v1, v[2:3], s[10:11] sc1
	s_waitcnt vmcnt(0)
